# Q-projection epilogue: rotary table loads of row groups 1..6 issued two groups ahead (3 rotating register sets, counted vmcnt)
# speedup vs baseline: 1.0060x; 1.0060x over previous
; __device__ __forceinline__ void store8(bf16_t* p, const f32x4& a, const f32x4& b) { u32x4 w; w.x = pk2(a[0], a[1]); w.y = pk2(a[2], a[3]); w.z = pk2(b[0], b[1]); w.w = pk2(b[2], b[3]); *(u32x4*)p = w; }
;     __device__ __forceinline__ void operator()(const f32x4 (&acc)[2][2][4][2], const pg8::Unit& u, int wr, int wc, int fr, int fq, int buf) const {
;     ...
;                     const int rl = ai * 128 + m * 16 + rloc0; const size_t row = (size_t)u.pm * 256 + rl; const float rsc = scr[rl];
; #pragma unroll
;                     for (int bj = 0; bj < 2; ++bj) {
;                         f32x4 v0 = acc[ai][bj][m][0] * rsc, v1 = acc[ai][bj][m][1] * rsc;
;                         if (kind == EK_Q) {
;                             const int cbase = u.pn * 256 + bj * 128 + wc * 32, d0 = cbase % 192; const bool rp = d0 >= 128; const int wcc = (d0 - 128) >> 5;
;                             if (rp && lat) {
;                                 const int t = (jt - 1) * 256 + rl; const int to = t * 32 + wcc * 16 + 8 * (fq & 1); const float sg = (fq < 2) ? -1.f : 1.f;
;                                 { const f32x4 ca = *(const f32x4*)(cs + to), sa = *(const f32x4*)(sn + to);
; #pragma unroll
;                                   for (int j = 0; j < 4; ++j) { const float pp = __shfl_xor(v0[j], 32); v0[j] = v0[j] * ca[j] + sg * pp * sa[j]; } }
;                                 { const f32x4 ca = *(const f32x4*)(cs + to + 4), sa = *(const f32x4*)(sn + to + 4);
; #pragma unroll
;                                   for (int j = 0; j < 4; ++j) { const float pp = __shfl_xor(v1[j], 32); v1[j] = v1[j] * ca[j] + sg * pp * sa[j]; } }
;                             }
;                             store8(Q + row * 768 + cbase + 8 * fq, v0, v1);
.LBB0_697:
	v_cvt_pk_bf16_f32 v118, v118, v119
	v_cvt_pk_bf16_f32 v119, v120, v121
	v_cvt_pk_bf16_f32 v120, v114, v115
	v_cvt_pk_bf16_f32 v121, v116, v117
	global_store_dwordx4 v[124:125], v[118:121], off offset:256
	ds_read_b32 v114, v165 offset:64
	v_add_u32_e32 v116, 16, v148
	v_add_u32_e32 v115, s71, v116
	v_lshl_or_b32 v120, v115, 5, v164
	s_and_b64 vcc, exec, s[4:5]
	s_waitcnt lgkmcnt(0)
	v_pk_mul_f32 v[112:113], v[112:113], v[114:115] op_sel_hi:[1,0]
	v_pk_mul_f32 v[118:119], v[110:111], v[114:115] op_sel_hi:[1,0]
	v_pk_mul_f32 v[108:109], v[108:109], v[114:115] op_sel_hi:[1,0]
	v_pk_mul_f32 v[110:111], v[106:107], v[114:115] op_sel_hi:[1,0]
	s_cbranch_vccnz .LBB0_699
	s_add_i32 s75, s70, 0xffffff80
	s_lshr_b32 s75, s75, 1
	v_add_u32_e32 v230, 16, v148
	v_add_u32_e32 v230, s71, v230
	v_lshl_or_b32 v230, v230, 5, v164
	v_add_u32_e32 v230, s75, v230
	v_ashrrev_i32_e32 v231, 31, v230
	v_lshlrev_b64 v[230:231], 2, v[230:231]
	v_lshl_add_u64 v[232:233], s[58:59], 0, v[230:231]
	global_load_dwordx4 v[182:185], v[232:233], off offset:16
	v_lshl_add_u64 v[232:233], s[58:59], 0, v[230:231]
	global_load_dwordx4 v[186:189], v[232:233], off
	v_lshl_add_u64 v[232:233], s[60:61], 0, v[230:231]
	global_load_dwordx4 v[190:193], v[232:233], off offset:16
	v_lshl_add_u64 v[232:233], s[60:61], 0, v[230:231]
	global_load_dwordx4 v[194:197], v[232:233], off
	v_add_u32_e32 v230, 32, v148
	v_add_u32_e32 v230, s71, v230
	v_lshl_or_b32 v230, v230, 5, v164
	v_add_u32_e32 v230, s75, v230
	v_ashrrev_i32_e32 v231, 31, v230
	v_lshlrev_b64 v[230:231], 2, v[230:231]
	v_lshl_add_u64 v[232:233], s[58:59], 0, v[230:231]
	global_load_dwordx4 v[198:201], v[232:233], off offset:16
	v_lshl_add_u64 v[232:233], s[58:59], 0, v[230:231]
	global_load_dwordx4 v[202:205], v[232:233], off
	v_lshl_add_u64 v[232:233], s[60:61], 0, v[230:231]
	global_load_dwordx4 v[206:209], v[232:233], off offset:16
	v_lshl_add_u64 v[232:233], s[60:61], 0, v[230:231]
	global_load_dwordx4 v[210:213], v[232:233], off
	v_add_u32_e32 v230, 48, v148
	v_add_u32_e32 v230, s71, v230
	v_lshl_or_b32 v230, v230, 5, v164
	v_add_u32_e32 v230, s75, v230
	v_ashrrev_i32_e32 v231, 31, v230
	v_lshlrev_b64 v[230:231], 2, v[230:231]
	v_lshl_add_u64 v[232:233], s[58:59], 0, v[230:231]
	global_load_dwordx4 v[214:217], v[232:233], off offset:16
	v_lshl_add_u64 v[232:233], s[58:59], 0, v[230:231]
	global_load_dwordx4 v[218:221], v[232:233], off
	v_lshl_add_u64 v[232:233], s[60:61], 0, v[230:231]
	global_load_dwordx4 v[222:225], v[232:233], off offset:16
	v_lshl_add_u64 v[232:233], s[60:61], 0, v[230:231]
	global_load_dwordx4 v[226:229], v[232:233], off
	v_and_b32_e32 v107, 64, v163
	v_xor_b32_e32 v106, 32, v163
	v_add_u32_e32 v107, 64, v107
	v_cmp_lt_i32_e32 vcc, v106, v107
	s_nop 1
	v_cndmask_b32_e32 v106, v163, v106, vcc
	v_lshlrev_b32_e32 v115, 2, v106
	ds_bpermute_b32 v117, v115, v112
	ds_bpermute_b32 v106, v115, v118
	ds_bpermute_b32 v107, v115, v119
	s_waitcnt lgkmcnt(0)
	v_mul_f32_e32 v117, v146, v117
	v_pk_mul_f32 v[106:107], v[146:147], v[106:107] op_sel_hi:[0,1]
	s_waitcnt vmcnt(8)
	v_pk_mul_f32 v[118:119], v[118:119], v[186:187]
	v_mul_f32_e32 v128, v196, v117
	ds_bpermute_b32 v117, v115, v113
	v_mov_b32_e32 v196, v113
	v_mov_b32_e32 v186, v189
	v_mul_f32_e32 v112, v112, v188
	v_pk_fma_f32 v[118:119], v[194:195], v[106:107], v[118:119]
	s_waitcnt lgkmcnt(0)
	v_mul_f32_e32 v187, v146, v117
	v_pk_mul_f32 v[186:187], v[196:197], v[186:187]
	ds_bpermute_b32 v117, v115, v108
	v_mov_b32_e32 v113, v186
	v_mov_b32_e32 v129, v187
	ds_bpermute_b32 v186, v115, v110
	ds_bpermute_b32 v187, v115, v111
	ds_bpermute_b32 v115, v115, v109
	s_waitcnt lgkmcnt(3)
	v_mul_f32_e32 v117, v146, v117
	v_pk_mul_f32 v[110:111], v[110:111], v[182:183]
	v_mul_f32_e32 v108, v108, v184
	s_waitcnt lgkmcnt(1)
	v_pk_mul_f32 v[182:183], v[146:147], v[186:187] op_sel_hi:[0,1]
	v_mul_f32_e32 v184, v192, v117
	s_waitcnt lgkmcnt(0)
	v_mul_f32_e32 v187, v146, v115
	v_mov_b32_e32 v192, v109
	v_mov_b32_e32 v186, v185
	v_pk_mul_f32 v[186:187], v[192:193], v[186:187]
	v_pk_fma_f32 v[110:111], v[190:191], v[182:183], v[110:111]
	v_mov_b32_e32 v109, v186
	v_mov_b32_e32 v185, v187
	v_pk_add_f32 v[108:109], v[108:109], v[184:185]
	v_pk_add_f32 v[112:113], v[112:113], v[128:129]
; __device__ __forceinline__ void store8(bf16_t* p, const f32x4& a, const f32x4& b) { u32x4 w; w.x = pk2(a[0], a[1]); w.y = pk2(a[2], a[3]); w.z = pk2(b[0], b[1]); w.w = pk2(b[2], b[3]); *(u32x4*)p = w; }
;     __device__ __forceinline__ void operator()(const f32x4 (&acc)[2][2][4][2], const pg8::Unit& u, int wr, int wc, int fr, int fq, int buf) const {
;     ...
;                     const int rl = ai * 128 + m * 16 + rloc0; const size_t row = (size_t)u.pm * 256 + rl; const float rsc = scr[rl];
; #pragma unroll
;                     for (int bj = 0; bj < 2; ++bj) {
;                         f32x4 v0 = acc[ai][bj][m][0] * rsc, v1 = acc[ai][bj][m][1] * rsc;
;                         if (kind == EK_Q) {
;                             const int cbase = u.pn * 256 + bj * 128 + wc * 32, d0 = cbase % 192; const bool rp = d0 >= 128; const int wcc = (d0 - 128) >> 5;
;                             if (rp && lat) {
;                                 const int t = (jt - 1) * 256 + rl; const int to = t * 32 + wcc * 16 + 8 * (fq & 1); const float sg = (fq < 2) ? -1.f : 1.f;
;                                 { const f32x4 ca = *(const f32x4*)(cs + to), sa = *(const f32x4*)(sn + to);
; #pragma unroll
;                                   for (int j = 0; j < 4; ++j) { const float pp = __shfl_xor(v0[j], 32); v0[j] = v0[j] * ca[j] + sg * pp * sa[j]; } }
;                                 { const f32x4 ca = *(const f32x4*)(cs + to + 4), sa = *(const f32x4*)(sn + to + 4);
; #pragma unroll
;                                   for (int j = 0; j < 4; ++j) { const float pp = __shfl_xor(v1[j], 32); v1[j] = v1[j] * ca[j] + sg * pp * sa[j]; } }
;                             }
;                             store8(Q + row * 768 + cbase + 8 * fq, v0, v1);
.LBB0_699:
	v_ashrrev_i32_e32 v117, 31, v116
	v_lshl_add_u64 v[106:107], s[66:67], 0, v[116:117]
	v_mad_u64_u32 v[116:117], s[78:79], v106, s50, v[122:123]
	v_mov_b32_e32 v106, v117
	v_mad_u64_u32 v[106:107], s[78:79], v107, s50, v[106:107]
	v_mov_b32_e32 v117, v106
	v_mov_b32_e32 v115, v114
	v_lshl_add_u64 v[106:107], s[68:69], 1, v[116:117]
	v_cvt_pk_bf16_f32 v116, v118, v119
	v_cvt_pk_bf16_f32 v119, v108, v109
	v_mov_b32_e32 v108, v114
	v_mov_b32_e32 v109, v114
	v_cvt_pk_bf16_f32 v117, v112, v113
	v_cvt_pk_bf16_f32 v118, v110, v111
	v_pk_mul_f32 v[104:105], v[104:105], v[108:109]
	v_pk_mul_f32 v[102:103], v[102:103], v[114:115]
	v_pk_mul_f32 v[100:101], v[100:101], v[108:109]
	s_and_b64 vcc, exec, s[6:7]
	v_pk_mul_f32 v[98:99], v[98:99], v[114:115]
	global_store_dwordx4 v[106:107], v[116:119], off
	s_cbranch_vccnz .LBB0_701
	s_add_i32 s75, s74, 0xffffff80
	s_lshr_b32 s75, s75, 1
	v_add_u32_e32 v230, 16, v148
	v_add_u32_e32 v230, s71, v230
	v_lshl_or_b32 v230, v230, 5, v164
	v_add_u32_e32 v230, s75, v230
	v_ashrrev_i32_e32 v231, 31, v230
	v_lshlrev_b64 v[230:231], 2, v[230:231]
	v_lshl_add_u64 v[232:233], s[58:59], 0, v[230:231]
	global_load_dwordx4 v[182:185], v[232:233], off offset:16
	v_lshl_add_u64 v[232:233], s[58:59], 0, v[230:231]
	global_load_dwordx4 v[186:189], v[232:233], off
	v_lshl_add_u64 v[232:233], s[60:61], 0, v[230:231]
	global_load_dwordx4 v[190:193], v[232:233], off offset:16
	v_lshl_add_u64 v[232:233], s[60:61], 0, v[230:231]
	global_load_dwordx4 v[194:197], v[232:233], off
	v_add_u32_e32 v230, 32, v148
	v_add_u32_e32 v230, s71, v230
	v_lshl_or_b32 v230, v230, 5, v164
	v_add_u32_e32 v230, s75, v230
	v_ashrrev_i32_e32 v231, 31, v230
	v_lshlrev_b64 v[230:231], 2, v[230:231]
	v_lshl_add_u64 v[232:233], s[58:59], 0, v[230:231]
	global_load_dwordx4 v[198:201], v[232:233], off offset:16
	v_lshl_add_u64 v[232:233], s[58:59], 0, v[230:231]
	global_load_dwordx4 v[202:205], v[232:233], off
	v_lshl_add_u64 v[232:233], s[60:61], 0, v[230:231]
	global_load_dwordx4 v[206:209], v[232:233], off offset:16
	v_lshl_add_u64 v[232:233], s[60:61], 0, v[230:231]
	global_load_dwordx4 v[210:213], v[232:233], off
	v_add_u32_e32 v230, 48, v148
	v_add_u32_e32 v230, s71, v230
	v_lshl_or_b32 v230, v230, 5, v164
	v_add_u32_e32 v230, s75, v230
	v_ashrrev_i32_e32 v231, 31, v230
	v_lshlrev_b64 v[230:231], 2, v[230:231]
	v_lshl_add_u64 v[232:233], s[58:59], 0, v[230:231]
	global_load_dwordx4 v[214:217], v[232:233], off offset:16
	v_lshl_add_u64 v[232:233], s[58:59], 0, v[230:231]
	global_load_dwordx4 v[218:221], v[232:233], off
	v_lshl_add_u64 v[232:233], s[60:61], 0, v[230:231]
	global_load_dwordx4 v[222:225], v[232:233], off offset:16
	v_lshl_add_u64 v[232:233], s[60:61], 0, v[230:231]
	global_load_dwordx4 v[226:229], v[232:233], off
	v_and_b32_e32 v121, 64, v163
	v_xor_b32_e32 v120, 32, v163
	v_add_u32_e32 v121, 64, v121
	v_cmp_lt_i32_e32 vcc, v120, v121
	s_nop 1
	v_cndmask_b32_e32 v120, v163, v120, vcc
	v_lshlrev_b32_e32 v128, 2, v120
	ds_bpermute_b32 v120, v128, v102
	ds_bpermute_b32 v121, v128, v103
	s_waitcnt vmcnt(8)
	v_pk_mul_f32 v[102:103], v[102:103], v[186:187]
	s_waitcnt lgkmcnt(0)
	v_pk_mul_f32 v[186:187], v[146:147], v[120:121] op_sel_hi:[0,1]
	ds_bpermute_b32 v120, v128, v104
	v_mul_f32_e32 v104, v104, v188
	v_pk_fma_f32 v[102:103], v[194:195], v[186:187], v[102:103]
	s_waitcnt lgkmcnt(0)
	v_mul_f32_e32 v188, v146, v120
	ds_bpermute_b32 v120, v128, v105
	v_mul_f32_e32 v188, v196, v188
	v_mov_b32_e32 v196, v105
	s_waitcnt lgkmcnt(0)
	v_mul_f32_e32 v121, v146, v120
	v_mov_b32_e32 v120, v189
	v_pk_mul_f32 v[120:121], v[196:197], v[120:121]
	s_nop 0
	v_mov_b32_e32 v105, v120
	v_mov_b32_e32 v189, v121
	ds_bpermute_b32 v120, v128, v98
	ds_bpermute_b32 v121, v128, v99
	v_pk_mul_f32 v[98:99], v[98:99], v[182:183]
	v_pk_add_f32 v[104:105], v[104:105], v[188:189]
	s_waitcnt lgkmcnt(0)
	v_pk_mul_f32 v[182:183], v[146:147], v[120:121] op_sel_hi:[0,1]
	ds_bpermute_b32 v120, v128, v100
	v_mul_f32_e32 v100, v100, v184
	v_pk_fma_f32 v[98:99], v[190:191], v[182:183], v[98:99]
	s_waitcnt lgkmcnt(0)
	v_mul_f32_e32 v184, v146, v120
	v_mul_f32_e32 v184, v192, v184
	ds_bpermute_b32 v192, v128, v101
	v_mov_b32_e32 v120, v185
	s_waitcnt lgkmcnt(0)
	v_mul_f32_e32 v121, v146, v192
	v_mov_b32_e32 v192, v101
	v_pk_mul_f32 v[192:193], v[192:193], v[120:121]
	s_nop 0
	v_mov_b32_e32 v101, v192
	v_mov_b32_e32 v185, v193
	v_pk_add_f32 v[100:101], v[100:101], v[184:185]
; __device__ __forceinline__ void store8(bf16_t* p, const f32x4& a, const f32x4& b) { u32x4 w; w.x = pk2(a[0], a[1]); w.y = pk2(a[2], a[3]); w.z = pk2(b[0], b[1]); w.w = pk2(b[2], b[3]); *(u32x4*)p = w; }
;     __device__ __forceinline__ void operator()(const f32x4 (&acc)[2][2][4][2], const pg8::Unit& u, int wr, int wc, int fr, int fq, int buf) const {
;     ...
;                     const int rl = ai * 128 + m * 16 + rloc0; const size_t row = (size_t)u.pm * 256 + rl; const float rsc = scr[rl];
; #pragma unroll
;                     for (int bj = 0; bj < 2; ++bj) {
;                         f32x4 v0 = acc[ai][bj][m][0] * rsc, v1 = acc[ai][bj][m][1] * rsc;
;                         if (kind == EK_Q) {
;                             const int cbase = u.pn * 256 + bj * 128 + wc * 32, d0 = cbase % 192; const bool rp = d0 >= 128; const int wcc = (d0 - 128) >> 5;
;                             if (rp && lat) {
;                                 const int t = (jt - 1) * 256 + rl; const int to = t * 32 + wcc * 16 + 8 * (fq & 1); const float sg = (fq < 2) ? -1.f : 1.f;
;                                 { const f32x4 ca = *(const f32x4*)(cs + to), sa = *(const f32x4*)(sn + to);
; #pragma unroll
;                                   for (int j = 0; j < 4; ++j) { const float pp = __shfl_xor(v0[j], 32); v0[j] = v0[j] * ca[j] + sg * pp * sa[j]; } }
;                                 { const f32x4 ca = *(const f32x4*)(cs + to + 4), sa = *(const f32x4*)(sn + to + 4);
; #pragma unroll
;                                   for (int j = 0; j < 4; ++j) { const float pp = __shfl_xor(v1[j], 32); v1[j] = v1[j] * ca[j] + sg * pp * sa[j]; } }
;                             }
;                             store8(Q + row * 768 + cbase + 8 * fq, v0, v1);
.LBB0_701:
	v_cvt_pk_bf16_f32 v102, v102, v103
	v_cvt_pk_bf16_f32 v103, v104, v105
	v_cvt_pk_bf16_f32 v104, v98, v99
	v_cvt_pk_bf16_f32 v105, v100, v101
	global_store_dwordx4 v[106:107], v[102:105], off offset:256
	ds_read_b32 v98, v165 offset:128
	v_add_u32_e32 v100, 32, v148
	v_add_u32_e32 v99, s71, v100
	v_lshl_or_b32 v104, v99, 5, v164
	s_and_b64 vcc, exec, s[4:5]
	s_waitcnt lgkmcnt(0)
	v_pk_mul_f32 v[96:97], v[96:97], v[98:99] op_sel_hi:[1,0]
	v_pk_mul_f32 v[102:103], v[94:95], v[98:99] op_sel_hi:[1,0]
	v_pk_mul_f32 v[92:93], v[92:93], v[98:99] op_sel_hi:[1,0]
	v_pk_mul_f32 v[94:95], v[90:91], v[98:99] op_sel_hi:[1,0]
	s_cbranch_vccnz .LBB0_703
	s_add_i32 s75, s70, 0xffffff80
	s_lshr_b32 s75, s75, 1
	v_add_u32_e32 v230, 0x80, v148
	v_add_u32_e32 v230, s71, v230
	v_lshl_or_b32 v230, v230, 5, v164
	v_add_u32_e32 v230, s75, v230
	v_ashrrev_i32_e32 v231, 31, v230
	v_lshlrev_b64 v[230:231], 2, v[230:231]
	v_lshl_add_u64 v[232:233], s[58:59], 0, v[230:231]
	global_load_dwordx4 v[182:185], v[232:233], off offset:16
	v_lshl_add_u64 v[232:233], s[58:59], 0, v[230:231]
	global_load_dwordx4 v[186:189], v[232:233], off
	v_lshl_add_u64 v[232:233], s[60:61], 0, v[230:231]
	global_load_dwordx4 v[190:193], v[232:233], off offset:16
	v_lshl_add_u64 v[232:233], s[60:61], 0, v[230:231]
	global_load_dwordx4 v[194:197], v[232:233], off
	v_and_b32_e32 v91, 64, v163
	v_xor_b32_e32 v90, 32, v163
	v_add_u32_e32 v91, 64, v91
	v_cmp_lt_i32_e32 vcc, v90, v91
	s_waitcnt vmcnt(10)
	v_mov_b32_e32 v124, v205
	v_cndmask_b32_e32 v90, v163, v90, vcc
	v_lshlrev_b32_e32 v99, 2, v90
	ds_bpermute_b32 v101, v99, v96
	ds_bpermute_b32 v90, v99, v102
	ds_bpermute_b32 v91, v99, v103
	v_pk_mul_f32 v[102:103], v[102:103], v[202:203]
	v_mul_f32_e32 v96, v96, v204
	s_waitcnt lgkmcnt(2)
	v_mul_f32_e32 v101, v146, v101
	v_mul_f32_e32 v202, v212, v101
	ds_bpermute_b32 v101, v99, v97
	v_mov_b32_e32 v212, v97
	s_waitcnt lgkmcnt(1)
	v_pk_mul_f32 v[90:91], v[146:147], v[90:91] op_sel_hi:[0,1]
	v_pk_fma_f32 v[102:103], v[210:211], v[90:91], v[102:103]
	s_waitcnt lgkmcnt(0)
	v_mul_f32_e32 v125, v146, v101
	v_pk_mul_f32 v[204:205], v[212:213], v[124:125]
	ds_bpermute_b32 v101, v99, v92
	v_mov_b32_e32 v97, v204
	v_mov_b32_e32 v203, v205
	ds_bpermute_b32 v204, v99, v94
	ds_bpermute_b32 v205, v99, v95
	ds_bpermute_b32 v99, v99, v93
	s_waitcnt lgkmcnt(3)
	v_mul_f32_e32 v101, v146, v101
	v_pk_mul_f32 v[94:95], v[94:95], v[198:199]
	v_mul_f32_e32 v92, v92, v200
	s_waitcnt lgkmcnt(1)
	v_pk_mul_f32 v[198:199], v[146:147], v[204:205] op_sel_hi:[0,1]
	v_mul_f32_e32 v200, v208, v101
	s_waitcnt lgkmcnt(0)
	v_mul_f32_e32 v205, v146, v99
	v_mov_b32_e32 v208, v93
	v_mov_b32_e32 v204, v201
	v_pk_mul_f32 v[204:205], v[208:209], v[204:205]
	v_pk_fma_f32 v[94:95], v[206:207], v[198:199], v[94:95]
	v_mov_b32_e32 v93, v204
	v_mov_b32_e32 v201, v205
	v_pk_add_f32 v[92:93], v[92:93], v[200:201]
	v_pk_add_f32 v[96:97], v[96:97], v[202:203]
.LBB0_703:
	v_ashrrev_i32_e32 v101, 31, v100
	v_lshl_add_u64 v[90:91], s[66:67], 0, v[100:101]
	v_mad_u64_u32 v[100:101], s[78:79], v90, s50, v[122:123]
	v_mov_b32_e32 v90, v101
	v_mad_u64_u32 v[90:91], s[78:79], v91, s50, v[90:91]
	v_mov_b32_e32 v101, v90
	v_mov_b32_e32 v99, v98
	v_lshl_add_u64 v[90:91], s[68:69], 1, v[100:101]
	v_cvt_pk_bf16_f32 v100, v102, v103
	v_cvt_pk_bf16_f32 v103, v92, v93
	v_mov_b32_e32 v92, v98
	v_mov_b32_e32 v93, v98
	v_cvt_pk_bf16_f32 v101, v96, v97
	v_cvt_pk_bf16_f32 v102, v94, v95
	v_pk_mul_f32 v[88:89], v[88:89], v[92:93]
	v_pk_mul_f32 v[86:87], v[86:87], v[98:99]
	v_pk_mul_f32 v[84:85], v[84:85], v[92:93]
	s_and_b64 vcc, exec, s[6:7]
	v_pk_mul_f32 v[82:83], v[82:83], v[98:99]
	global_store_dwordx4 v[90:91], v[100:103], off
	s_cbranch_vccnz .LBB0_705
	s_add_i32 s75, s74, 0xffffff80
	s_lshr_b32 s75, s75, 1
	v_add_u32_e32 v230, 0x80, v148
	v_add_u32_e32 v230, s71, v230
	v_lshl_or_b32 v230, v230, 5, v164
	v_add_u32_e32 v230, s75, v230
	v_ashrrev_i32_e32 v231, 31, v230
	v_lshlrev_b64 v[230:231], 2, v[230:231]
	v_lshl_add_u64 v[232:233], s[58:59], 0, v[230:231]
	global_load_dwordx4 v[182:185], v[232:233], off offset:16
	v_lshl_add_u64 v[232:233], s[58:59], 0, v[230:231]
	global_load_dwordx4 v[186:189], v[232:233], off
	v_lshl_add_u64 v[232:233], s[60:61], 0, v[230:231]
	global_load_dwordx4 v[190:193], v[232:233], off offset:16
	v_lshl_add_u64 v[232:233], s[60:61], 0, v[230:231]
	global_load_dwordx4 v[194:197], v[232:233], off
	v_and_b32_e32 v109, 64, v163
	v_xor_b32_e32 v108, 32, v163
	v_add_u32_e32 v109, 64, v109
	v_cmp_lt_i32_e32 vcc, v108, v109
	s_nop 1
	v_cndmask_b32_e32 v108, v163, v108, vcc
	v_lshlrev_b32_e32 v110, 2, v108
	ds_bpermute_b32 v108, v110, v86
	ds_bpermute_b32 v109, v110, v87
	s_waitcnt vmcnt(10)
	v_pk_mul_f32 v[86:87], v[86:87], v[202:203]
	s_waitcnt lgkmcnt(0)
	v_pk_mul_f32 v[202:203], v[146:147], v[108:109] op_sel_hi:[0,1]
	ds_bpermute_b32 v108, v110, v88
	v_mul_f32_e32 v88, v88, v204
	v_pk_fma_f32 v[86:87], v[210:211], v[202:203], v[86:87]
	s_waitcnt lgkmcnt(0)
	v_mul_f32_e32 v204, v146, v108
	v_mul_f32_e32 v204, v212, v204
	ds_bpermute_b32 v212, v110, v89
	v_mov_b32_e32 v108, v205
	s_waitcnt lgkmcnt(0)
	v_mul_f32_e32 v109, v146, v212
	v_mov_b32_e32 v212, v89
	v_pk_mul_f32 v[212:213], v[212:213], v[108:109]
	s_nop 0
	v_mov_b32_e32 v89, v212
	v_mov_b32_e32 v205, v213
	ds_bpermute_b32 v212, v110, v82
	ds_bpermute_b32 v213, v110, v83
	v_pk_mul_f32 v[82:83], v[82:83], v[198:199]
	v_pk_add_f32 v[88:89], v[88:89], v[204:205]
	s_waitcnt lgkmcnt(0)
	v_pk_mul_f32 v[198:199], v[146:147], v[212:213] op_sel_hi:[0,1]
	ds_bpermute_b32 v212, v110, v84
	v_mul_f32_e32 v84, v84, v200
	v_pk_fma_f32 v[82:83], v[206:207], v[198:199], v[82:83]
	s_waitcnt lgkmcnt(0)
	v_mul_f32_e32 v200, v146, v212
	v_mul_f32_e32 v200, v208, v200
	ds_bpermute_b32 v208, v110, v85
	v_mov_b32_e32 v212, v201
	s_waitcnt lgkmcnt(0)
	v_mul_f32_e32 v213, v146, v208
	v_mov_b32_e32 v208, v85
	v_pk_mul_f32 v[208:209], v[208:209], v[212:213]
	s_nop 0
	v_mov_b32_e32 v85, v208
	v_mov_b32_e32 v201, v209
	v_pk_add_f32 v[84:85], v[84:85], v[200:201]
; __device__ __forceinline__ void store8(bf16_t* p, const f32x4& a, const f32x4& b) { u32x4 w; w.x = pk2(a[0], a[1]); w.y = pk2(a[2], a[3]); w.z = pk2(b[0], b[1]); w.w = pk2(b[2], b[3]); *(u32x4*)p = w; }
;     __device__ __forceinline__ void operator()(const f32x4 (&acc)[2][2][4][2], const pg8::Unit& u, int wr, int wc, int fr, int fq, int buf) const {
;     ...
;                     const int rl = ai * 128 + m * 16 + rloc0; const size_t row = (size_t)u.pm * 256 + rl; const float rsc = scr[rl];
; #pragma unroll
;                     for (int bj = 0; bj < 2; ++bj) {
;                         f32x4 v0 = acc[ai][bj][m][0] * rsc, v1 = acc[ai][bj][m][1] * rsc;
;                         if (kind == EK_Q) {
;                             const int cbase = u.pn * 256 + bj * 128 + wc * 32, d0 = cbase % 192; const bool rp = d0 >= 128; const int wcc = (d0 - 128) >> 5;
;                             if (rp && lat) {
;                                 const int t = (jt - 1) * 256 + rl; const int to = t * 32 + wcc * 16 + 8 * (fq & 1); const float sg = (fq < 2) ? -1.f : 1.f;
;                                 { const f32x4 ca = *(const f32x4*)(cs + to), sa = *(const f32x4*)(sn + to);
; #pragma unroll
;                                   for (int j = 0; j < 4; ++j) { const float pp = __shfl_xor(v0[j], 32); v0[j] = v0[j] * ca[j] + sg * pp * sa[j]; } }
;                                 { const f32x4 ca = *(const f32x4*)(cs + to + 4), sa = *(const f32x4*)(sn + to + 4);
; #pragma unroll
;                                   for (int j = 0; j < 4; ++j) { const float pp = __shfl_xor(v1[j], 32); v1[j] = v1[j] * ca[j] + sg * pp * sa[j]; } }
;                             }
;                             store8(Q + row * 768 + cbase + 8 * fq, v0, v1);
.LBB0_705:
	v_cvt_pk_bf16_f32 v86, v86, v87
	v_cvt_pk_bf16_f32 v87, v88, v89
	v_cvt_pk_bf16_f32 v88, v82, v83
	v_cvt_pk_bf16_f32 v89, v84, v85
	global_store_dwordx4 v[90:91], v[86:89], off offset:256
	ds_read_b32 v82, v165 offset:192
	v_add_u32_e32 v84, 48, v148
	v_add_u32_e32 v83, s71, v84
	v_lshl_or_b32 v88, v83, 5, v164
	s_and_b64 vcc, exec, s[4:5]
	s_waitcnt lgkmcnt(0)
	v_pk_mul_f32 v[80:81], v[80:81], v[82:83] op_sel_hi:[1,0]
	v_pk_mul_f32 v[86:87], v[78:79], v[82:83] op_sel_hi:[1,0]
	v_pk_mul_f32 v[76:77], v[76:77], v[82:83] op_sel_hi:[1,0]
	v_pk_mul_f32 v[78:79], v[74:75], v[82:83] op_sel_hi:[1,0]
	s_cbranch_vccnz .LBB0_707
	s_add_i32 s75, s70, 0xffffff80
	s_lshr_b32 s75, s75, 1
	v_add_u32_e32 v230, 0x90, v148
	v_add_u32_e32 v230, s71, v230
	v_lshl_or_b32 v230, v230, 5, v164
	v_add_u32_e32 v230, s75, v230
	v_ashrrev_i32_e32 v231, 31, v230
	v_lshlrev_b64 v[230:231], 2, v[230:231]
	v_lshl_add_u64 v[232:233], s[58:59], 0, v[230:231]
	global_load_dwordx4 v[198:201], v[232:233], off offset:16
	v_lshl_add_u64 v[232:233], s[58:59], 0, v[230:231]
	global_load_dwordx4 v[202:205], v[232:233], off
	v_lshl_add_u64 v[232:233], s[60:61], 0, v[230:231]
	global_load_dwordx4 v[206:209], v[232:233], off offset:16
	v_lshl_add_u64 v[232:233], s[60:61], 0, v[230:231]
	global_load_dwordx4 v[210:213], v[232:233], off
	v_and_b32_e32 v75, 64, v163
	v_xor_b32_e32 v74, 32, v163
	v_add_u32_e32 v75, 64, v75
	v_cmp_lt_i32_e32 vcc, v74, v75
	s_waitcnt vmcnt(12)
	v_mov_b32_e32 v106, v221
	v_cndmask_b32_e32 v74, v163, v74, vcc
	v_lshlrev_b32_e32 v83, 2, v74
	ds_bpermute_b32 v85, v83, v80
	ds_bpermute_b32 v74, v83, v86
	ds_bpermute_b32 v75, v83, v87
	v_pk_mul_f32 v[86:87], v[86:87], v[218:219]
	v_mul_f32_e32 v80, v80, v220
	s_waitcnt lgkmcnt(2)
	v_mul_f32_e32 v85, v146, v85
	v_mul_f32_e32 v218, v228, v85
	ds_bpermute_b32 v85, v83, v81
	v_mov_b32_e32 v228, v81
	s_waitcnt lgkmcnt(1)
	v_pk_mul_f32 v[74:75], v[146:147], v[74:75] op_sel_hi:[0,1]
	v_pk_fma_f32 v[86:87], v[226:227], v[74:75], v[86:87]
	s_waitcnt lgkmcnt(0)
	v_mul_f32_e32 v107, v146, v85
	v_pk_mul_f32 v[220:221], v[228:229], v[106:107]
	ds_bpermute_b32 v85, v83, v76
	v_mov_b32_e32 v81, v220
	v_mov_b32_e32 v219, v221
	ds_bpermute_b32 v220, v83, v78
	ds_bpermute_b32 v221, v83, v79
	ds_bpermute_b32 v83, v83, v77
	s_waitcnt lgkmcnt(3)
	v_mul_f32_e32 v85, v146, v85
	v_pk_mul_f32 v[78:79], v[78:79], v[214:215]
	v_mul_f32_e32 v76, v76, v216
	s_waitcnt lgkmcnt(1)
	v_pk_mul_f32 v[214:215], v[146:147], v[220:221] op_sel_hi:[0,1]
	v_mul_f32_e32 v216, v224, v85
	s_waitcnt lgkmcnt(0)
	v_mul_f32_e32 v221, v146, v83
	v_mov_b32_e32 v224, v77
	v_mov_b32_e32 v220, v217
	v_pk_mul_f32 v[220:221], v[224:225], v[220:221]
	v_pk_fma_f32 v[78:79], v[222:223], v[214:215], v[78:79]
	v_mov_b32_e32 v77, v220
	v_mov_b32_e32 v217, v221
	v_pk_add_f32 v[76:77], v[76:77], v[216:217]
	v_pk_add_f32 v[80:81], v[80:81], v[218:219]
.LBB0_707:
	v_ashrrev_i32_e32 v85, 31, v84
	v_lshl_add_u64 v[74:75], s[66:67], 0, v[84:85]
	v_mad_u64_u32 v[84:85], s[78:79], v74, s50, v[122:123]
	v_mov_b32_e32 v74, v85
	v_mad_u64_u32 v[74:75], s[78:79], v75, s50, v[74:75]
	v_mov_b32_e32 v85, v74
	v_mov_b32_e32 v83, v82
	v_lshl_add_u64 v[74:75], s[68:69], 1, v[84:85]
	v_cvt_pk_bf16_f32 v84, v86, v87
	v_cvt_pk_bf16_f32 v87, v76, v77
	v_mov_b32_e32 v76, v82
	v_mov_b32_e32 v77, v82
	v_cvt_pk_bf16_f32 v85, v80, v81
	v_cvt_pk_bf16_f32 v86, v78, v79
	v_pk_mul_f32 v[72:73], v[72:73], v[76:77]
	v_pk_mul_f32 v[70:71], v[70:71], v[82:83]
	v_pk_mul_f32 v[68:69], v[68:69], v[76:77]
	s_and_b64 vcc, exec, s[6:7]
	v_pk_mul_f32 v[66:67], v[66:67], v[82:83]
	global_store_dwordx4 v[74:75], v[84:87], off
	s_cbranch_vccnz .LBB0_709
	s_add_i32 s75, s74, 0xffffff80
	s_lshr_b32 s75, s75, 1
	v_add_u32_e32 v230, 0x90, v148
	v_add_u32_e32 v230, s71, v230
	v_lshl_or_b32 v230, v230, 5, v164
	v_add_u32_e32 v230, s75, v230
	v_ashrrev_i32_e32 v231, 31, v230
	v_lshlrev_b64 v[230:231], 2, v[230:231]
	v_lshl_add_u64 v[232:233], s[58:59], 0, v[230:231]
	global_load_dwordx4 v[198:201], v[232:233], off offset:16
	v_lshl_add_u64 v[232:233], s[58:59], 0, v[230:231]
	global_load_dwordx4 v[202:205], v[232:233], off
	v_lshl_add_u64 v[232:233], s[60:61], 0, v[230:231]
	global_load_dwordx4 v[206:209], v[232:233], off offset:16
	v_lshl_add_u64 v[232:233], s[60:61], 0, v[230:231]
	global_load_dwordx4 v[210:213], v[232:233], off
	v_and_b32_e32 v93, 64, v163
	v_xor_b32_e32 v92, 32, v163
	v_add_u32_e32 v93, 64, v93
	v_cmp_lt_i32_e32 vcc, v92, v93
	s_nop 1
	v_cndmask_b32_e32 v92, v163, v92, vcc
	v_lshlrev_b32_e32 v94, 2, v92
	ds_bpermute_b32 v92, v94, v70
	ds_bpermute_b32 v93, v94, v71
	s_waitcnt vmcnt(12)
	v_pk_mul_f32 v[70:71], v[70:71], v[218:219]
	s_waitcnt lgkmcnt(0)
	v_pk_mul_f32 v[218:219], v[146:147], v[92:93] op_sel_hi:[0,1]
	ds_bpermute_b32 v92, v94, v72
	v_mul_f32_e32 v72, v72, v220
	v_pk_fma_f32 v[70:71], v[226:227], v[218:219], v[70:71]
	s_waitcnt lgkmcnt(0)
	v_mul_f32_e32 v220, v146, v92
	v_mul_f32_e32 v220, v228, v220
	ds_bpermute_b32 v228, v94, v73
	v_mov_b32_e32 v92, v221
	s_waitcnt lgkmcnt(0)
	v_mul_f32_e32 v93, v146, v228
	v_mov_b32_e32 v228, v73
	v_pk_mul_f32 v[228:229], v[228:229], v[92:93]
	s_nop 0
	v_mov_b32_e32 v73, v228
	v_mov_b32_e32 v221, v229
	ds_bpermute_b32 v228, v94, v66
	ds_bpermute_b32 v229, v94, v67
	v_pk_mul_f32 v[66:67], v[66:67], v[214:215]
	v_pk_add_f32 v[72:73], v[72:73], v[220:221]
	s_waitcnt lgkmcnt(0)
	v_pk_mul_f32 v[214:215], v[146:147], v[228:229] op_sel_hi:[0,1]
	ds_bpermute_b32 v228, v94, v68
	v_mul_f32_e32 v68, v68, v216
	v_pk_fma_f32 v[66:67], v[222:223], v[214:215], v[66:67]
	s_waitcnt lgkmcnt(0)
	v_mul_f32_e32 v216, v146, v228
	v_mul_f32_e32 v216, v224, v216
	ds_bpermute_b32 v224, v94, v69
	v_mov_b32_e32 v228, v217
	s_waitcnt lgkmcnt(0)
	v_mul_f32_e32 v229, v146, v224
	v_mov_b32_e32 v224, v69
	v_pk_mul_f32 v[224:225], v[224:225], v[228:229]
	s_nop 0
	v_mov_b32_e32 v69, v224
	v_mov_b32_e32 v217, v225
	v_pk_add_f32 v[68:69], v[68:69], v[216:217]
; __device__ __forceinline__ void store8(bf16_t* p, const f32x4& a, const f32x4& b) { u32x4 w; w.x = pk2(a[0], a[1]); w.y = pk2(a[2], a[3]); w.z = pk2(b[0], b[1]); w.w = pk2(b[2], b[3]); *(u32x4*)p = w; }
;     __device__ __forceinline__ void operator()(const f32x4 (&acc)[2][2][4][2], const pg8::Unit& u, int wr, int wc, int fr, int fq, int buf) const {
;     ...
;                     const int rl = ai * 128 + m * 16 + rloc0; const size_t row = (size_t)u.pm * 256 + rl; const float rsc = scr[rl];
; #pragma unroll
;                     for (int bj = 0; bj < 2; ++bj) {
;                         f32x4 v0 = acc[ai][bj][m][0] * rsc, v1 = acc[ai][bj][m][1] * rsc;
;                         if (kind == EK_Q) {
;                             const int cbase = u.pn * 256 + bj * 128 + wc * 32, d0 = cbase % 192; const bool rp = d0 >= 128; const int wcc = (d0 - 128) >> 5;
;                             if (rp && lat) {
;                                 const int t = (jt - 1) * 256 + rl; const int to = t * 32 + wcc * 16 + 8 * (fq & 1); const float sg = (fq < 2) ? -1.f : 1.f;
;                                 { const f32x4 ca = *(const f32x4*)(cs + to), sa = *(const f32x4*)(sn + to);
; #pragma unroll
;                                   for (int j = 0; j < 4; ++j) { const float pp = __shfl_xor(v0[j], 32); v0[j] = v0[j] * ca[j] + sg * pp * sa[j]; } }
;                                 { const f32x4 ca = *(const f32x4*)(cs + to + 4), sa = *(const f32x4*)(sn + to + 4);
; #pragma unroll
;                                   for (int j = 0; j < 4; ++j) { const float pp = __shfl_xor(v1[j], 32); v1[j] = v1[j] * ca[j] + sg * pp * sa[j]; } }
;                             }
;                             store8(Q + row * 768 + cbase + 8 * fq, v0, v1);
.LBB0_709:
	v_cvt_pk_bf16_f32 v70, v70, v71
	v_cvt_pk_bf16_f32 v71, v72, v73
	v_cvt_pk_bf16_f32 v72, v66, v67
	v_cvt_pk_bf16_f32 v73, v68, v69
	global_store_dwordx4 v[74:75], v[70:73], off offset:256
	ds_read_b32 v66, v165 offset:512
	v_add_u32_e32 v68, 0x80, v148
	v_add_u32_e32 v67, s71, v68
	v_lshl_or_b32 v72, v67, 5, v164
	s_and_b64 vcc, exec, s[4:5]
	s_waitcnt lgkmcnt(0)
	v_pk_mul_f32 v[64:65], v[64:65], v[66:67] op_sel_hi:[1,0]
	v_pk_mul_f32 v[70:71], v[62:63], v[66:67] op_sel_hi:[1,0]
	v_pk_mul_f32 v[60:61], v[60:61], v[66:67] op_sel_hi:[1,0]
	v_pk_mul_f32 v[62:63], v[58:59], v[66:67] op_sel_hi:[1,0]
	s_cbranch_vccnz .LBB0_711
	s_add_i32 s75, s70, 0xffffff80
	s_lshr_b32 s75, s75, 1
	v_add_u32_e32 v230, 0xa0, v148
	v_add_u32_e32 v230, s71, v230
	v_lshl_or_b32 v230, v230, 5, v164
	v_add_u32_e32 v230, s75, v230
	v_ashrrev_i32_e32 v231, 31, v230
	v_lshlrev_b64 v[230:231], 2, v[230:231]
	v_lshl_add_u64 v[232:233], s[58:59], 0, v[230:231]
	global_load_dwordx4 v[214:217], v[232:233], off offset:16
	v_lshl_add_u64 v[232:233], s[58:59], 0, v[230:231]
	global_load_dwordx4 v[218:221], v[232:233], off
	v_lshl_add_u64 v[232:233], s[60:61], 0, v[230:231]
	global_load_dwordx4 v[222:225], v[232:233], off offset:16
	v_lshl_add_u64 v[232:233], s[60:61], 0, v[230:231]
	global_load_dwordx4 v[226:229], v[232:233], off
	v_and_b32_e32 v59, 64, v163
	v_xor_b32_e32 v58, 32, v163
	v_add_u32_e32 v59, 64, v59
	v_cmp_lt_i32_e32 vcc, v58, v59
	s_waitcnt vmcnt(12)
	v_mov_b32_e32 v90, v189
	v_cndmask_b32_e32 v58, v163, v58, vcc
	v_lshlrev_b32_e32 v67, 2, v58
	ds_bpermute_b32 v69, v67, v64
	ds_bpermute_b32 v58, v67, v70
	ds_bpermute_b32 v59, v67, v71
	v_pk_mul_f32 v[70:71], v[70:71], v[186:187]
	v_mul_f32_e32 v64, v64, v188
	s_waitcnt lgkmcnt(2)
	v_mul_f32_e32 v69, v146, v69
	v_mul_f32_e32 v186, v196, v69
	ds_bpermute_b32 v69, v67, v65
	v_mov_b32_e32 v196, v65
	s_waitcnt lgkmcnt(1)
	v_pk_mul_f32 v[58:59], v[146:147], v[58:59] op_sel_hi:[0,1]
	v_pk_fma_f32 v[70:71], v[194:195], v[58:59], v[70:71]
	s_waitcnt lgkmcnt(0)
	v_mul_f32_e32 v91, v146, v69
	v_pk_mul_f32 v[188:189], v[196:197], v[90:91]
	ds_bpermute_b32 v69, v67, v60
	v_mov_b32_e32 v65, v188
	v_mov_b32_e32 v187, v189
	ds_bpermute_b32 v188, v67, v62
	ds_bpermute_b32 v189, v67, v63
	ds_bpermute_b32 v67, v67, v61
	s_waitcnt lgkmcnt(3)
	v_mul_f32_e32 v69, v146, v69
	v_pk_mul_f32 v[62:63], v[62:63], v[182:183]
	v_mul_f32_e32 v60, v60, v184
	s_waitcnt lgkmcnt(1)
	v_pk_mul_f32 v[182:183], v[146:147], v[188:189] op_sel_hi:[0,1]
	v_mul_f32_e32 v184, v192, v69
	s_waitcnt lgkmcnt(0)
	v_mul_f32_e32 v189, v146, v67
	v_mov_b32_e32 v192, v61
	v_mov_b32_e32 v188, v185
	v_pk_mul_f32 v[188:189], v[192:193], v[188:189]
	v_pk_fma_f32 v[62:63], v[190:191], v[182:183], v[62:63]
	v_mov_b32_e32 v61, v188
	v_mov_b32_e32 v185, v189
	v_pk_add_f32 v[60:61], v[60:61], v[184:185]
	v_pk_add_f32 v[64:65], v[64:65], v[186:187]
.LBB0_711:
	v_ashrrev_i32_e32 v69, 31, v68
	v_lshl_add_u64 v[58:59], s[66:67], 0, v[68:69]
	v_mad_u64_u32 v[68:69], s[78:79], v58, s50, v[122:123]
	v_mov_b32_e32 v58, v69
	v_mad_u64_u32 v[58:59], s[78:79], v59, s50, v[58:59]
	v_mov_b32_e32 v69, v58
	v_mov_b32_e32 v67, v66
	v_lshl_add_u64 v[58:59], s[68:69], 1, v[68:69]
	v_cvt_pk_bf16_f32 v68, v70, v71
	v_cvt_pk_bf16_f32 v71, v60, v61
	v_mov_b32_e32 v60, v66
	v_mov_b32_e32 v61, v66
	v_cvt_pk_bf16_f32 v69, v64, v65
	v_cvt_pk_bf16_f32 v70, v62, v63
	v_pk_mul_f32 v[56:57], v[56:57], v[60:61]
	v_pk_mul_f32 v[54:55], v[54:55], v[66:67]
	v_pk_mul_f32 v[52:53], v[52:53], v[60:61]
	s_and_b64 vcc, exec, s[6:7]
	v_pk_mul_f32 v[50:51], v[50:51], v[66:67]
	global_store_dwordx4 v[58:59], v[68:71], off
	s_cbranch_vccnz .LBB0_713
	s_add_i32 s75, s74, 0xffffff80
	s_lshr_b32 s75, s75, 1
	v_add_u32_e32 v230, 0xa0, v148
	v_add_u32_e32 v230, s71, v230
	v_lshl_or_b32 v230, v230, 5, v164
	v_add_u32_e32 v230, s75, v230
	v_ashrrev_i32_e32 v231, 31, v230
	v_lshlrev_b64 v[230:231], 2, v[230:231]
	v_lshl_add_u64 v[232:233], s[58:59], 0, v[230:231]
	global_load_dwordx4 v[214:217], v[232:233], off offset:16
	v_lshl_add_u64 v[232:233], s[58:59], 0, v[230:231]
	global_load_dwordx4 v[218:221], v[232:233], off
	v_lshl_add_u64 v[232:233], s[60:61], 0, v[230:231]
	global_load_dwordx4 v[222:225], v[232:233], off offset:16
	v_lshl_add_u64 v[232:233], s[60:61], 0, v[230:231]
	global_load_dwordx4 v[226:229], v[232:233], off
	v_and_b32_e32 v77, 64, v163
	v_xor_b32_e32 v76, 32, v163
	v_add_u32_e32 v77, 64, v77
	v_cmp_lt_i32_e32 vcc, v76, v77
	s_nop 1
	v_cndmask_b32_e32 v76, v163, v76, vcc
	v_lshlrev_b32_e32 v78, 2, v76
	ds_bpermute_b32 v76, v78, v54
	ds_bpermute_b32 v77, v78, v55
	s_waitcnt vmcnt(12)
	v_pk_mul_f32 v[54:55], v[54:55], v[186:187]
	s_waitcnt lgkmcnt(0)
	v_pk_mul_f32 v[186:187], v[146:147], v[76:77] op_sel_hi:[0,1]
	ds_bpermute_b32 v76, v78, v56
	v_mul_f32_e32 v56, v56, v188
	v_pk_fma_f32 v[54:55], v[194:195], v[186:187], v[54:55]
	s_waitcnt lgkmcnt(0)
	v_mul_f32_e32 v188, v146, v76
	v_mul_f32_e32 v188, v196, v188
	ds_bpermute_b32 v196, v78, v57
	v_mov_b32_e32 v76, v189
	s_waitcnt lgkmcnt(0)
	v_mul_f32_e32 v77, v146, v196
	v_mov_b32_e32 v196, v57
	v_pk_mul_f32 v[196:197], v[196:197], v[76:77]
	s_nop 0
	v_mov_b32_e32 v57, v196
	v_mov_b32_e32 v189, v197
	ds_bpermute_b32 v196, v78, v50
	ds_bpermute_b32 v197, v78, v51
	v_pk_mul_f32 v[50:51], v[50:51], v[182:183]
	v_pk_add_f32 v[56:57], v[56:57], v[188:189]
	s_waitcnt lgkmcnt(0)
	v_pk_mul_f32 v[182:183], v[146:147], v[196:197] op_sel_hi:[0,1]
	ds_bpermute_b32 v196, v78, v52
	v_mul_f32_e32 v52, v52, v184
	v_pk_fma_f32 v[50:51], v[190:191], v[182:183], v[50:51]
	s_waitcnt lgkmcnt(0)
	v_mul_f32_e32 v184, v146, v196
	v_mul_f32_e32 v184, v192, v184
	ds_bpermute_b32 v192, v78, v53
	v_mov_b32_e32 v196, v185
	s_waitcnt lgkmcnt(0)
	v_mul_f32_e32 v197, v146, v192
	v_mov_b32_e32 v192, v53
	v_pk_mul_f32 v[192:193], v[192:193], v[196:197]
	s_nop 0
	v_mov_b32_e32 v53, v192
	v_mov_b32_e32 v185, v193
	v_pk_add_f32 v[52:53], v[52:53], v[184:185]
; __device__ __forceinline__ void store8(bf16_t* p, const f32x4& a, const f32x4& b) { u32x4 w; w.x = pk2(a[0], a[1]); w.y = pk2(a[2], a[3]); w.z = pk2(b[0], b[1]); w.w = pk2(b[2], b[3]); *(u32x4*)p = w; }
;     __device__ __forceinline__ void operator()(const f32x4 (&acc)[2][2][4][2], const pg8::Unit& u, int wr, int wc, int fr, int fq, int buf) const {
;     ...
;                     const int rl = ai * 128 + m * 16 + rloc0; const size_t row = (size_t)u.pm * 256 + rl; const float rsc = scr[rl];
; #pragma unroll
;                     for (int bj = 0; bj < 2; ++bj) {
;                         f32x4 v0 = acc[ai][bj][m][0] * rsc, v1 = acc[ai][bj][m][1] * rsc;
;                         if (kind == EK_Q) {
;                             const int cbase = u.pn * 256 + bj * 128 + wc * 32, d0 = cbase % 192; const bool rp = d0 >= 128; const int wcc = (d0 - 128) >> 5;
;                             if (rp && lat) {
;                                 const int t = (jt - 1) * 256 + rl; const int to = t * 32 + wcc * 16 + 8 * (fq & 1); const float sg = (fq < 2) ? -1.f : 1.f;
;                                 { const f32x4 ca = *(const f32x4*)(cs + to), sa = *(const f32x4*)(sn + to);
; #pragma unroll
;                                   for (int j = 0; j < 4; ++j) { const float pp = __shfl_xor(v0[j], 32); v0[j] = v0[j] * ca[j] + sg * pp * sa[j]; } }
;                                 { const f32x4 ca = *(const f32x4*)(cs + to + 4), sa = *(const f32x4*)(sn + to + 4);
; #pragma unroll
;                                   for (int j = 0; j < 4; ++j) { const float pp = __shfl_xor(v1[j], 32); v1[j] = v1[j] * ca[j] + sg * pp * sa[j]; } }
;                             }
;                             store8(Q + row * 768 + cbase + 8 * fq, v0, v1);
.LBB0_713:
	v_cvt_pk_bf16_f32 v54, v54, v55
	v_cvt_pk_bf16_f32 v55, v56, v57
	v_cvt_pk_bf16_f32 v56, v50, v51
	v_cvt_pk_bf16_f32 v57, v52, v53
	global_store_dwordx4 v[58:59], v[54:57], off offset:256
	ds_read_b32 v50, v165 offset:576
	v_add_u32_e32 v52, 0x90, v148
	v_add_u32_e32 v51, s71, v52
	v_lshl_or_b32 v56, v51, 5, v164
	s_and_b64 vcc, exec, s[4:5]
	s_waitcnt lgkmcnt(0)
	v_pk_mul_f32 v[48:49], v[48:49], v[50:51] op_sel_hi:[1,0]
	v_pk_mul_f32 v[54:55], v[46:47], v[50:51] op_sel_hi:[1,0]
	v_pk_mul_f32 v[44:45], v[44:45], v[50:51] op_sel_hi:[1,0]
	v_pk_mul_f32 v[46:47], v[42:43], v[50:51] op_sel_hi:[1,0]
	s_cbranch_vccnz .LBB0_715
	s_add_i32 s75, s70, 0xffffff80
	s_lshr_b32 s75, s75, 1
	v_and_b32_e32 v43, 64, v163
	v_xor_b32_e32 v42, 32, v163
	v_add_u32_e32 v43, 64, v43
	v_cmp_lt_i32_e32 vcc, v42, v43
	s_waitcnt vmcnt(8)
	v_mov_b32_e32 v74, v205
	v_cndmask_b32_e32 v42, v163, v42, vcc
	v_lshlrev_b32_e32 v51, 2, v42
	ds_bpermute_b32 v53, v51, v48
	ds_bpermute_b32 v42, v51, v54
	ds_bpermute_b32 v43, v51, v55
	v_pk_mul_f32 v[54:55], v[54:55], v[202:203]
	v_mul_f32_e32 v48, v48, v204
	s_waitcnt lgkmcnt(2)
	v_mul_f32_e32 v53, v146, v53
	v_mul_f32_e32 v202, v212, v53
	ds_bpermute_b32 v53, v51, v49
	v_mov_b32_e32 v212, v49
	s_waitcnt lgkmcnt(1)
	v_pk_mul_f32 v[42:43], v[146:147], v[42:43] op_sel_hi:[0,1]
	v_pk_fma_f32 v[54:55], v[210:211], v[42:43], v[54:55]
	s_waitcnt lgkmcnt(0)
	v_mul_f32_e32 v75, v146, v53
	v_pk_mul_f32 v[204:205], v[212:213], v[74:75]
	ds_bpermute_b32 v53, v51, v44
	v_mov_b32_e32 v49, v204
	v_mov_b32_e32 v203, v205
	ds_bpermute_b32 v204, v51, v46
	ds_bpermute_b32 v205, v51, v47
	ds_bpermute_b32 v51, v51, v45
	s_waitcnt lgkmcnt(3)
	v_mul_f32_e32 v53, v146, v53
	v_pk_mul_f32 v[46:47], v[46:47], v[198:199]
	v_mul_f32_e32 v44, v44, v200
	s_waitcnt lgkmcnt(1)
	v_pk_mul_f32 v[198:199], v[146:147], v[204:205] op_sel_hi:[0,1]
	v_mul_f32_e32 v200, v208, v53
	s_waitcnt lgkmcnt(0)
	v_mul_f32_e32 v205, v146, v51
	v_mov_b32_e32 v208, v45
	v_mov_b32_e32 v204, v201
	v_pk_mul_f32 v[204:205], v[208:209], v[204:205]
	v_pk_fma_f32 v[46:47], v[206:207], v[198:199], v[46:47]
	v_mov_b32_e32 v45, v204
	v_mov_b32_e32 v201, v205
	v_pk_add_f32 v[44:45], v[44:45], v[200:201]
	v_pk_add_f32 v[48:49], v[48:49], v[202:203]
.LBB0_715:
	v_ashrrev_i32_e32 v53, 31, v52
	v_lshl_add_u64 v[42:43], s[66:67], 0, v[52:53]
	v_mad_u64_u32 v[52:53], s[78:79], v42, s50, v[122:123]
	v_mov_b32_e32 v42, v53
	v_mad_u64_u32 v[42:43], s[78:79], v43, s50, v[42:43]
	v_mov_b32_e32 v53, v42
	v_mov_b32_e32 v51, v50
	v_lshl_add_u64 v[42:43], s[68:69], 1, v[52:53]
	v_cvt_pk_bf16_f32 v52, v54, v55
	v_cvt_pk_bf16_f32 v55, v44, v45
	v_mov_b32_e32 v44, v50
	v_mov_b32_e32 v45, v50
	v_cvt_pk_bf16_f32 v53, v48, v49
	v_cvt_pk_bf16_f32 v54, v46, v47
	v_pk_mul_f32 v[40:41], v[40:41], v[44:45]
	v_pk_mul_f32 v[38:39], v[38:39], v[50:51]
	v_pk_mul_f32 v[36:37], v[36:37], v[44:45]
	s_and_b64 vcc, exec, s[6:7]
	v_pk_mul_f32 v[34:35], v[34:35], v[50:51]
	global_store_dwordx4 v[42:43], v[52:55], off
	s_cbranch_vccnz .LBB0_717
	s_add_i32 s75, s74, 0xffffff80
	s_lshr_b32 s75, s75, 1
	v_and_b32_e32 v61, 64, v163
	v_xor_b32_e32 v60, 32, v163
	v_add_u32_e32 v61, 64, v61
	v_cmp_lt_i32_e32 vcc, v60, v61
	s_nop 1
	v_cndmask_b32_e32 v60, v163, v60, vcc
	v_lshlrev_b32_e32 v62, 2, v60
	ds_bpermute_b32 v60, v62, v38
	ds_bpermute_b32 v61, v62, v39
	s_waitcnt vmcnt(8)
	v_pk_mul_f32 v[38:39], v[38:39], v[202:203]
	s_waitcnt lgkmcnt(0)
	v_pk_mul_f32 v[202:203], v[146:147], v[60:61] op_sel_hi:[0,1]
	ds_bpermute_b32 v60, v62, v40
	v_mul_f32_e32 v40, v40, v204
	v_pk_fma_f32 v[38:39], v[210:211], v[202:203], v[38:39]
	s_waitcnt lgkmcnt(0)
	v_mul_f32_e32 v204, v146, v60
	v_mul_f32_e32 v204, v212, v204
	ds_bpermute_b32 v212, v62, v41
	v_mov_b32_e32 v60, v205
	s_waitcnt lgkmcnt(0)
	v_mul_f32_e32 v61, v146, v212
	v_mov_b32_e32 v212, v41
	v_pk_mul_f32 v[212:213], v[212:213], v[60:61]
	s_nop 0
	v_mov_b32_e32 v41, v212
	v_mov_b32_e32 v205, v213
	ds_bpermute_b32 v212, v62, v34
	ds_bpermute_b32 v213, v62, v35
	v_pk_mul_f32 v[34:35], v[34:35], v[198:199]
	v_pk_add_f32 v[40:41], v[40:41], v[204:205]
	s_waitcnt lgkmcnt(0)
	v_pk_mul_f32 v[198:199], v[146:147], v[212:213] op_sel_hi:[0,1]
	ds_bpermute_b32 v212, v62, v36
	v_mul_f32_e32 v36, v36, v200
	v_pk_fma_f32 v[34:35], v[206:207], v[198:199], v[34:35]
	s_waitcnt lgkmcnt(0)
	v_mul_f32_e32 v200, v146, v212
	v_mul_f32_e32 v200, v208, v200
	ds_bpermute_b32 v208, v62, v37
	v_mov_b32_e32 v212, v201
	s_waitcnt lgkmcnt(0)
	v_mul_f32_e32 v213, v146, v208
	v_mov_b32_e32 v208, v37
	v_pk_mul_f32 v[208:209], v[208:209], v[212:213]
	s_nop 0
	v_mov_b32_e32 v37, v208
	v_mov_b32_e32 v201, v209
	v_pk_add_f32 v[36:37], v[36:37], v[200:201]
; __device__ __forceinline__ void store8(bf16_t* p, const f32x4& a, const f32x4& b) { u32x4 w; w.x = pk2(a[0], a[1]); w.y = pk2(a[2], a[3]); w.z = pk2(b[0], b[1]); w.w = pk2(b[2], b[3]); *(u32x4*)p = w; }
;     __device__ __forceinline__ void operator()(const f32x4 (&acc)[2][2][4][2], const pg8::Unit& u, int wr, int wc, int fr, int fq, int buf) const {
;     ...
;                     const int rl = ai * 128 + m * 16 + rloc0; const size_t row = (size_t)u.pm * 256 + rl; const float rsc = scr[rl];
; #pragma unroll
;                     for (int bj = 0; bj < 2; ++bj) {
;                         f32x4 v0 = acc[ai][bj][m][0] * rsc, v1 = acc[ai][bj][m][1] * rsc;
;                         if (kind == EK_Q) {
;                             const int cbase = u.pn * 256 + bj * 128 + wc * 32, d0 = cbase % 192; const bool rp = d0 >= 128; const int wcc = (d0 - 128) >> 5;
;                             if (rp && lat) {
;                                 const int t = (jt - 1) * 256 + rl; const int to = t * 32 + wcc * 16 + 8 * (fq & 1); const float sg = (fq < 2) ? -1.f : 1.f;
;                                 { const f32x4 ca = *(const f32x4*)(cs + to), sa = *(const f32x4*)(sn + to);
; #pragma unroll
;                                   for (int j = 0; j < 4; ++j) { const float pp = __shfl_xor(v0[j], 32); v0[j] = v0[j] * ca[j] + sg * pp * sa[j]; } }
;                                 { const f32x4 ca = *(const f32x4*)(cs + to + 4), sa = *(const f32x4*)(sn + to + 4);
; #pragma unroll
;                                   for (int j = 0; j < 4; ++j) { const float pp = __shfl_xor(v1[j], 32); v1[j] = v1[j] * ca[j] + sg * pp * sa[j]; } }
;                             }
;                             store8(Q + row * 768 + cbase + 8 * fq, v0, v1);
.LBB0_717:
	v_cvt_pk_bf16_f32 v38, v38, v39
	v_cvt_pk_bf16_f32 v39, v40, v41
	v_cvt_pk_bf16_f32 v40, v34, v35
	v_cvt_pk_bf16_f32 v41, v36, v37
	global_store_dwordx4 v[42:43], v[38:41], off offset:256
	ds_read_b32 v34, v165 offset:640
	v_add_u32_e32 v36, 0xa0, v148
	v_add_u32_e32 v35, s71, v36
	v_lshl_or_b32 v40, v35, 5, v164
	s_and_b64 vcc, exec, s[4:5]
	s_waitcnt lgkmcnt(0)
	v_pk_mul_f32 v[32:33], v[32:33], v[34:35] op_sel_hi:[1,0]
	v_pk_mul_f32 v[38:39], v[30:31], v[34:35] op_sel_hi:[1,0]
	v_pk_mul_f32 v[28:29], v[28:29], v[34:35] op_sel_hi:[1,0]
	v_pk_mul_f32 v[30:31], v[26:27], v[34:35] op_sel_hi:[1,0]
	s_cbranch_vccnz .LBB0_719
	s_add_i32 s75, s70, 0xffffff80
	s_lshr_b32 s75, s75, 1
	v_and_b32_e32 v27, 64, v163
	v_xor_b32_e32 v26, 32, v163
	v_add_u32_e32 v27, 64, v27
	v_cmp_lt_i32_e32 vcc, v26, v27
	s_waitcnt vmcnt(4)
	v_mov_b32_e32 v58, v221
	v_cndmask_b32_e32 v26, v163, v26, vcc
	v_lshlrev_b32_e32 v35, 2, v26
	ds_bpermute_b32 v37, v35, v32
	ds_bpermute_b32 v26, v35, v38
	ds_bpermute_b32 v27, v35, v39
	v_pk_mul_f32 v[38:39], v[38:39], v[218:219]
	v_mul_f32_e32 v32, v32, v220
	s_waitcnt lgkmcnt(2)
	v_mul_f32_e32 v37, v146, v37
	v_mul_f32_e32 v218, v228, v37
	ds_bpermute_b32 v37, v35, v33
	v_mov_b32_e32 v228, v33
	s_waitcnt lgkmcnt(1)
	v_pk_mul_f32 v[26:27], v[146:147], v[26:27] op_sel_hi:[0,1]
	v_pk_fma_f32 v[38:39], v[226:227], v[26:27], v[38:39]
	s_waitcnt lgkmcnt(0)
	v_mul_f32_e32 v59, v146, v37
	v_pk_mul_f32 v[220:221], v[228:229], v[58:59]
	ds_bpermute_b32 v37, v35, v28
	v_mov_b32_e32 v33, v220
	v_mov_b32_e32 v219, v221
	ds_bpermute_b32 v220, v35, v30
	ds_bpermute_b32 v221, v35, v31
	ds_bpermute_b32 v35, v35, v29
	s_waitcnt lgkmcnt(3)
	v_mul_f32_e32 v37, v146, v37
	v_pk_mul_f32 v[30:31], v[30:31], v[214:215]
	v_mul_f32_e32 v28, v28, v216
	s_waitcnt lgkmcnt(1)
	v_pk_mul_f32 v[214:215], v[146:147], v[220:221] op_sel_hi:[0,1]
	v_mul_f32_e32 v216, v224, v37
	s_waitcnt lgkmcnt(0)
	v_mul_f32_e32 v221, v146, v35
	v_mov_b32_e32 v224, v29
	v_mov_b32_e32 v220, v217
	v_pk_mul_f32 v[220:221], v[224:225], v[220:221]
	v_pk_fma_f32 v[30:31], v[222:223], v[214:215], v[30:31]
	v_mov_b32_e32 v29, v220
	v_mov_b32_e32 v217, v221
	v_pk_add_f32 v[28:29], v[28:29], v[216:217]
	v_pk_add_f32 v[32:33], v[32:33], v[218:219]
.LBB0_719:
	v_ashrrev_i32_e32 v37, 31, v36
	v_lshl_add_u64 v[26:27], s[66:67], 0, v[36:37]
	v_mad_u64_u32 v[36:37], s[78:79], v26, s50, v[122:123]
	v_mov_b32_e32 v26, v37
	v_mad_u64_u32 v[26:27], s[78:79], v27, s50, v[26:27]
	v_mov_b32_e32 v37, v26
	v_mov_b32_e32 v35, v34
	v_lshl_add_u64 v[26:27], s[68:69], 1, v[36:37]
	v_cvt_pk_bf16_f32 v36, v38, v39
	v_cvt_pk_bf16_f32 v39, v28, v29
	v_mov_b32_e32 v28, v34
	v_mov_b32_e32 v29, v34
	v_cvt_pk_bf16_f32 v37, v32, v33
	v_cvt_pk_bf16_f32 v38, v30, v31
	v_pk_mul_f32 v[24:25], v[24:25], v[28:29]
	v_pk_mul_f32 v[22:23], v[22:23], v[34:35]
	v_pk_mul_f32 v[20:21], v[20:21], v[28:29]
	s_and_b64 vcc, exec, s[6:7]
	v_pk_mul_f32 v[18:19], v[18:19], v[34:35]
	global_store_dwordx4 v[26:27], v[36:39], off
	s_cbranch_vccnz .LBB0_721
	s_add_i32 s75, s74, 0xffffff80
	s_lshr_b32 s75, s75, 1
	v_and_b32_e32 v45, 64, v163
	v_xor_b32_e32 v44, 32, v163
	v_add_u32_e32 v45, 64, v45
	v_cmp_lt_i32_e32 vcc, v44, v45
	s_nop 1
	v_cndmask_b32_e32 v44, v163, v44, vcc
	v_lshlrev_b32_e32 v46, 2, v44
	ds_bpermute_b32 v44, v46, v22
	ds_bpermute_b32 v45, v46, v23
	s_waitcnt vmcnt(4)
	v_pk_mul_f32 v[22:23], v[22:23], v[218:219]
	s_waitcnt lgkmcnt(0)
	v_pk_mul_f32 v[218:219], v[146:147], v[44:45] op_sel_hi:[0,1]
	ds_bpermute_b32 v44, v46, v24
	v_mul_f32_e32 v24, v24, v220
	v_pk_fma_f32 v[22:23], v[226:227], v[218:219], v[22:23]
	s_waitcnt lgkmcnt(0)
	v_mul_f32_e32 v220, v146, v44
	v_mul_f32_e32 v220, v228, v220
	ds_bpermute_b32 v228, v46, v25
	v_mov_b32_e32 v44, v221
	s_waitcnt lgkmcnt(0)
	v_mul_f32_e32 v45, v146, v228
	v_mov_b32_e32 v228, v25
	v_pk_mul_f32 v[228:229], v[228:229], v[44:45]
	s_nop 0
	v_mov_b32_e32 v25, v228
	v_mov_b32_e32 v221, v229
	ds_bpermute_b32 v228, v46, v18
	ds_bpermute_b32 v229, v46, v19
	v_pk_mul_f32 v[18:19], v[18:19], v[214:215]
	v_pk_add_f32 v[24:25], v[24:25], v[220:221]
	s_waitcnt lgkmcnt(0)
	v_pk_mul_f32 v[214:215], v[146:147], v[228:229] op_sel_hi:[0,1]
	ds_bpermute_b32 v228, v46, v20
	v_mul_f32_e32 v20, v20, v216
	v_pk_fma_f32 v[18:19], v[222:223], v[214:215], v[18:19]
	s_waitcnt lgkmcnt(0)
	v_mul_f32_e32 v216, v146, v228
	v_mul_f32_e32 v216, v224, v216
	ds_bpermute_b32 v224, v46, v21
	v_mov_b32_e32 v228, v217
	s_waitcnt lgkmcnt(0)
	v_mul_f32_e32 v229, v146, v224
	v_mov_b32_e32 v224, v21
	v_pk_mul_f32 v[224:225], v[224:225], v[228:229]
	s_nop 0
	v_mov_b32_e32 v21, v224
	v_mov_b32_e32 v217, v225
	v_pk_add_f32 v[20:21], v[20:21], v[216:217]
